# delta recurrence consumer loop: the four late A fragments (ds_read -> wait -> mfma one at a time into one quad) are read early into free VGPRs
# baseline (speedup 1.0000x reference)
; __device__ __forceinline__ void delta_rec_task(const Params& P, LAS unsigned char* lds, int b, int h, int tid) {
;     ...
;         for (int c = 0; c < NC; ++c) {
;             LAS unsigned char* buf = lds + (c & 1) * DR_BUF;
;             const int vb = wave;
;             bf16x8 SB[8];
; #pragma unroll
;             for (int s = 0; s < 8; ++s) { const int kb = s >> 1, o = 8 * (s & 1); SB[s] = pack8(S[kb][o], S[kb][o + 1], S[kb][o + 2], S[kb][o + 3], S[kb][o + 4], S[kb][o + 5], S[kb][o + 6], S[kb][o + 7]); }
;             f32x16 X1, P1;
; #pragma unroll
;             for (int r = 0; r < 16; ++r) { X1[r] = 0.f; P1[r] = 0.f; }
;             const LAS bf16* KB = (const LAS bf16*)(buf + DR_KB) + n * 136 + 8 * hh; const LAS bf16* QD = (const LAS bf16*)(buf + DR_QD) + n * 136 + 8 * hh;
; #pragma unroll
;             for (int s = 0; s < 8; ++s) { X1 = __builtin_amdgcn_mfma_f32_32x32x16_bf16(*(const LAS bf16x8*)(KB + 16 * s), SB[s], X1, 0, 0, 0);
;                 P1 = __builtin_amdgcn_mfma_f32_32x32x16_bf16(*(const LAS bf16x8*)(QD + 16 * s), SB[s], P1, 0, 0, 0); }
;             const LAS float* VB = (const LAS float*)(buf + DR_VB) + 32 * vb + n;
;             float Y[16];
; #pragma unroll
;             for (int r = 0; r < 16; ++r) Y[r] = VB[((r & 3) + 8 * (r >> 2) + 4 * hh) * 132] - X1[r];
;             const bf16x8 YB0 = pack8(Y[0], Y[1], Y[2], Y[3], Y[4], Y[5], Y[6], Y[7]), YB1 = pack8(Y[8], Y[9], Y[10], Y[11], Y[12], Y[13], Y[14], Y[15]);
;             f32x16 VN;
; #pragma unroll
;             for (int r = 0; r < 16; ++r) VN[r] = 0.f;
;             const LAS bf16* TI = (const LAS bf16*)(buf + DR_TI) + n * 40 + 8 * hh; const LAS bf16* AT = (const LAS bf16*)(buf + DR_AT) + n * 40 + 8 * hh;
;             VN = __builtin_amdgcn_mfma_f32_32x32x16_bf16(*(const LAS bf16x8*)TI, YB0, VN, 0, 0, 0);
;             VN = __builtin_amdgcn_mfma_f32_32x32x16_bf16(*(const LAS bf16x8*)(TI + 16), YB1, VN, 0, 0, 0);
;             const bf16x8 VB0 = pack8(VN[0], VN[1], VN[2], VN[3], VN[4], VN[5], VN[6], VN[7]), VB1 = pack8(VN[8], VN[9], VN[10], VN[11], VN[12], VN[13], VN[14], VN[15]);
;             P1 = __builtin_amdgcn_mfma_f32_32x32x16_bf16(*(const LAS bf16x8*)AT, VB0, P1, 0, 0, 0);
;             P1 = __builtin_amdgcn_mfma_f32_32x32x16_bf16(*(const LAS bf16x8*)(AT + 16), VB1, P1, 0, 0, 0);
;             const float egl = *(const LAS float*)(buf + DR_EGL);
.LBB0_1833:
	s_and_b32 s4, s3, 1
	s_mul_i32 s5, s4, 0xc210
	s_add_i32 s5, s5, 0
	v_add3_u32 v136, s5, v117, v118
	ds_read_b128 v[64:67], v136
	ds_read_b128 v[96:99], v136 offset:32
	v_cvt_pk_bf16_f32 v80, v48, v49
	v_cvt_pk_bf16_f32 v81, v50, v51
	v_cvt_pk_bf16_f32 v82, v52, v53
	v_cvt_pk_bf16_f32 v83, v54, v55
	ds_read_b128 v[84:87], v136 offset:8704
	ds_read_b128 v[100:103], v136 offset:8736
	s_waitcnt lgkmcnt(3)
	v_mfma_f32_32x32x16_bf16 v[64:79], v[64:67], v[80:83], 0
	v_cvt_pk_bf16_f32 v104, v56, v57
	v_cvt_pk_bf16_f32 v105, v58, v59
	v_cvt_pk_bf16_f32 v106, v60, v61
	v_cvt_pk_bf16_f32 v107, v62, v63
	v_cvt_pk_bf16_f32 v108, v32, v33
	v_cvt_pk_bf16_f32 v109, v34, v35
	v_cvt_pk_bf16_f32 v110, v36, v37
	s_waitcnt vmcnt(0) lgkmcnt(1)
	v_mfma_f32_32x32x16_bf16 v[80:95], v[84:87], v[80:83], 0
	v_cvt_pk_bf16_f32 v111, v38, v39
	v_cvt_pk_bf16_f32 v120, v16, v17
	v_cvt_pk_bf16_f32 v121, v18, v19
	v_cvt_pk_bf16_f32 v122, v20, v21
	v_cvt_pk_bf16_f32 v123, v22, v23
	v_lshl_add_u32 v137, v112, 2, s5
	v_add3_u32 v162, v137, v115, v114
	v_mfma_f32_32x32x16_bf16 v[64:79], v[96:99], v[104:107], v[64:79]
	v_cvt_pk_bf16_f32 v96, v40, v41
	v_cvt_pk_bf16_f32 v97, v42, v43
	v_cvt_pk_bf16_f32 v98, v44, v45
	v_cvt_pk_bf16_f32 v99, v46, v47
	v_mov_b32_e32 v144, s5
	v_add3_u32 v161, s5, v119, v118
	v_add_u32_e32 v163, 0x8000, v162
	s_waitcnt lgkmcnt(0)
	v_mfma_f32_32x32x16_bf16 v[80:95], v[100:103], v[104:107], v[80:95]
	ds_read_b128 v[100:103], v136 offset:64
	ds_read_b128 v[104:107], v136 offset:96
	v_add_u32_e32 v164, 0x8400, v162
	v_add_u32_e32 v165, 0x9000, v162
	v_add_u32_e32 v168, 0x9400, v162
	v_add_u32_e32 v169, 0xa000, v162
	v_add_u32_e32 v170, 0xa400, v162
	v_add_u32_e32 v171, 0xb000, v162
	s_waitcnt lgkmcnt(1)
	v_mfma_f32_32x32x16_bf16 v[64:79], v[100:103], v[108:111], v[64:79]
	ds_read_b128 v[100:103], v136 offset:8768
	ds_read_b128 v[124:127], v136 offset:8800
	v_add_u32_e32 v172, 0xb400, v162
	s_mulk_i32 s4, 0x4200
	s_add_i32 s3, s3, 1
	s_cmp_lg_u32 s3, 64
	s_waitcnt lgkmcnt(1)
	v_mfma_f32_32x32x16_bf16 v[80:95], v[100:103], v[108:111], v[80:95]
	v_cvt_pk_bf16_f32 v100, v24, v25
	v_cvt_pk_bf16_f32 v101, v26, v27
	v_cvt_pk_bf16_f32 v102, v28, v29
	v_cvt_pk_bf16_f32 v103, v30, v31
	v_cvt_pk_bf16_f32 v108, v8, v9
	v_cvt_pk_bf16_f32 v109, v10, v11
	v_cvt_pk_bf16_f32 v110, v12, v13
	v_mfma_f32_32x32x16_bf16 v[64:79], v[104:107], v[96:99], v[64:79]
	v_cvt_pk_bf16_f32 v104, v0, v1
	v_cvt_pk_bf16_f32 v105, v2, v3
	v_cvt_pk_bf16_f32 v106, v4, v5
	v_cvt_pk_bf16_f32 v107, v6, v7
	v_cvt_pk_bf16_f32 v111, v14, v15
	s_waitcnt lgkmcnt(0)
	v_mfma_f32_32x32x16_bf16 v[80:95], v[124:127], v[96:99], v[80:95]
	ds_read_b128 v[96:99], v136 offset:128
	ds_read_b128 v[124:127], v136 offset:160
	s_waitcnt lgkmcnt(1)
	v_mfma_f32_32x32x16_bf16 v[64:79], v[96:99], v[120:123], v[64:79]
	ds_read_b128 v[96:99], v136 offset:8832
	ds_read_b128 v[128:131], v136 offset:8864
	s_waitcnt lgkmcnt(2)
	v_mfma_f32_32x32x16_bf16 v[64:79], v[124:127], v[100:103], v[64:79]
	s_waitcnt lgkmcnt(1)
	v_mfma_f32_32x32x16_bf16 v[80:95], v[96:99], v[120:123], v[80:95]
	ds_read_b128 v[96:99], v136 offset:8896
	ds_read_b128 v[120:123], v136 offset:192
	ds_read_b128 v[132:135], v136 offset:224
	ds_read_b128 v[124:127], v136 offset:8928
	ds_read_b128 v[136:139], v161 offset:27680
	ds_read_b128 v[140:143], v161 offset:30208
	ds_read_b32 v160, v144 offset:49664
	ds_read_b128 v[144:147], v161 offset:17408
	ds_read_b128 v[148:151], v161 offset:19968
	s_waitcnt lgkmcnt(2)
	v_pk_mul_f32 v[62:63], v[62:63], v[160:161] op_sel_hi:[1,0]
	v_pk_mul_f32 v[60:61], v[60:61], v[160:161] op_sel_hi:[1,0]
	v_mfma_f32_32x32x16_bf16 v[64:79], v[120:123], v[104:107], v[64:79]
	v_mul_f32_e64 v58, v58, v160
	v_mul_f32_e64 v59, v59, v160
	v_mul_f32_e64 v56, v56, v160
	v_mul_f32_e64 v57, v57, v160
	v_mul_f32_e64 v54, v54, v160
	v_mul_f32_e64 v55, v55, v160
	v_pk_mul_f32 v[52:53], v[52:53], v[160:161] op_sel_hi:[1,0]
	v_pk_mul_f32 v[50:51], v[50:51], v[160:161] op_sel_hi:[1,0]
	v_pk_mul_f32 v[48:49], v[48:49], v[160:161] op_sel_hi:[1,0]
	v_pk_mul_f32 v[46:47], v[46:47], v[160:161] op_sel_hi:[1,0]
	v_mfma_f32_32x32x16_bf16 v[80:95], v[128:131], v[100:103], v[80:95]
	ds_read_b128 v[128:131], v161 offset:22528
	ds_read_b128 v[152:155], v161 offset:25088
	ds_read_b128 v[100:103], v161 offset:27648
	ds_read_b128 v[156:159], v161 offset:25120
	ds_read2_b32 v[120:121], v163 offset1:132
	ds_read2_b32 v[122:123], v164 offset0:8 offset1:140
	v_pk_mul_f32 v[44:45], v[44:45], v[160:161] op_sel_hi:[1,0]
	v_pk_mul_f32 v[42:43], v[42:43], v[160:161] op_sel_hi:[1,0]
	v_pk_mul_f32 v[40:41], v[40:41], v[160:161] op_sel_hi:[1,0]
	v_pk_mul_f32 v[38:39], v[38:39], v[160:161] op_sel_hi:[1,0]
	v_pk_mul_f32 v[36:37], v[36:37], v[160:161] op_sel_hi:[1,0]
	v_mfma_f32_32x32x16_bf16 v[64:79], v[132:135], v[108:111], v[64:79]
	v_mul_f32_e64 v34, v34, v160
	v_mul_f32_e64 v35, v35, v160
	v_mul_f32_e64 v32, v32, v160
	v_mul_f32_e64 v33, v33, v160
	v_mul_f32_e64 v30, v30, v160
	v_mul_f32_e64 v31, v31, v160
	v_pk_mul_f32 v[28:29], v[28:29], v[160:161] op_sel_hi:[1,0]
	v_pk_mul_f32 v[26:27], v[26:27], v[160:161] op_sel_hi:[1,0]
	v_pk_mul_f32 v[24:25], v[24:25], v[160:161] op_sel_hi:[1,0]
	v_pk_mul_f32 v[22:23], v[22:23], v[160:161] op_sel_hi:[1,0]
	v_mfma_f32_32x32x16_bf16 v[80:95], v[96:99], v[104:107], v[80:95]
	ds_read2_b32 v[96:97], v165 offset0:32 offset1:164
	ds_read2_b32 v[98:99], v168 offset0:40 offset1:172
	ds_read2_b32 v[104:105], v169 offset0:64 offset1:196
	ds_read2_b32 v[162:163], v170 offset0:72 offset1:204
	ds_read2_b32 v[164:165], v171 offset0:96 offset1:228
	ds_read2_b32 v[168:169], v172 offset0:104 offset1:236
	ds_read_b128 v[176:179], v161 offset:17440
	ds_read_b128 v[180:183], v161 offset:20000
	ds_read_b128 v[184:187], v161 offset:22560
	ds_read_b128 v[188:191], v161 offset:30240
	s_waitcnt lgkmcnt(11)
; #define LAS __attribute__((address_space(3)))
; #define DR_BAR() do { asm volatile("s_waitcnt lgkmcnt(0)" ::: "memory"); __builtin_amdgcn_s_barrier(); asm volatile("" ::: "memory"); } while (0)
; __device__ __forceinline__ void delta_rec_task(const Params& P, LAS unsigned char* lds, int b, int h, int tid) {
;     ...
;             for (int r = 0; r < 16; ++r) Y[r] = VB[((r & 3) + 8 * (r >> 2) + 4 * hh) * 132] - X1[r];
;             const bf16x8 YB0 = pack8(Y[0], Y[1], Y[2], Y[3], Y[4], Y[5], Y[6], Y[7]), YB1 = pack8(Y[8], Y[9], Y[10], Y[11], Y[12], Y[13], Y[14], Y[15]);
;             f32x16 VN;
; #pragma unroll
;             for (int r = 0; r < 16; ++r) VN[r] = 0.f;
;             const LAS bf16* TI = (const LAS bf16*)(buf + DR_TI) + n * 40 + 8 * hh; const LAS bf16* AT = (const LAS bf16*)(buf + DR_AT) + n * 40 + 8 * hh;
;             VN = __builtin_amdgcn_mfma_f32_32x32x16_bf16(*(const LAS bf16x8*)TI, YB0, VN, 0, 0, 0);
;             VN = __builtin_amdgcn_mfma_f32_32x32x16_bf16(*(const LAS bf16x8*)(TI + 16), YB1, VN, 0, 0, 0);
;             const bf16x8 VB0 = pack8(VN[0], VN[1], VN[2], VN[3], VN[4], VN[5], VN[6], VN[7]), VB1 = pack8(VN[8], VN[9], VN[10], VN[11], VN[12], VN[13], VN[14], VN[15]);
;             P1 = __builtin_amdgcn_mfma_f32_32x32x16_bf16(*(const LAS bf16x8*)AT, VB0, P1, 0, 0, 0);
;             P1 = __builtin_amdgcn_mfma_f32_32x32x16_bf16(*(const LAS bf16x8*)(AT + 16), VB1, P1, 0, 0, 0);
;             const float egl = *(const LAS float*)(buf + DR_EGL);
;             const LAS bf16* KDT = (const LAS bf16*)(buf + DR_KDT) + n * 40 + 8 * hh;
; #pragma unroll
;             for (int kb = 0; kb < 4; ++kb) {
; #pragma unroll
;                 for (int r = 0; r < 16; ++r) S[kb][r] *= egl;
;                 S[kb] = __builtin_amdgcn_mfma_f32_32x32x16_bf16(*(const LAS bf16x8*)(KDT + kb * 32 * 40), VB0, S[kb], 0, 0, 0);
;                 S[kb] = __builtin_amdgcn_mfma_f32_32x32x16_bf16(*(const LAS bf16x8*)(KDT + kb * 32 * 40 + 16), VB1, S[kb], 0, 0, 0); }
;             LAS float* op = (LAS float*)(lds + DR_OB) + (c & 1) * 32 * 132 + 4 * hh * 132 + 32 * vb + n;
; #pragma unroll
;             for (int r = 0; r < 16; ++r) op[((r & 3) + 8 * (r >> 2)) * 132] = P1[r];
;             DR_BAR();
	v_pk_add_f32 v[64:65], v[120:121], v[64:65] neg_lo:[0,1] neg_hi:[0,1]
	s_waitcnt lgkmcnt(10)
	v_pk_add_f32 v[66:67], v[122:123], v[66:67] neg_lo:[0,1] neg_hi:[0,1]
	s_waitcnt lgkmcnt(9)
	v_pk_add_f32 v[68:69], v[96:97], v[68:69] neg_lo:[0,1] neg_hi:[0,1]
	s_waitcnt lgkmcnt(8)
	v_pk_add_f32 v[70:71], v[98:99], v[70:71] neg_lo:[0,1] neg_hi:[0,1]
	v_cvt_pk_bf16_f32 v64, v64, v65
	v_cvt_pk_bf16_f32 v65, v66, v67
	v_cvt_pk_bf16_f32 v66, v68, v69
	v_cvt_pk_bf16_f32 v67, v70, v71
	v_mfma_f32_32x32x16_bf16 v[80:95], v[124:127], v[108:111], v[80:95]
	s_waitcnt lgkmcnt(7)
	v_add_f32_e64 v72, v104, -v72
	v_add_f32_e64 v73, v105, -v73
	s_waitcnt lgkmcnt(5)
	v_add_f32_e64 v68, v164, -v76
	v_add_f32_e64 v69, v165, -v77
	s_waitcnt lgkmcnt(4)
	v_pk_add_f32 v[70:71], v[168:169], v[78:79] neg_lo:[0,1] neg_hi:[0,1]
	v_pk_mul_f32 v[20:21], v[20:21], v[160:161] op_sel_hi:[1,0]
	v_pk_mul_f32 v[18:19], v[18:19], v[160:161] op_sel_hi:[1,0]
	v_pk_mul_f32 v[16:17], v[16:17], v[160:161] op_sel_hi:[1,0]
	v_pk_mul_f32 v[14:15], v[14:15], v[160:161] op_sel_hi:[1,0]
	v_mfma_f32_32x32x16_bf16 v[96:111], v[100:103], v[64:67], 0
	v_add_f32_e64 v66, v162, -v74
	v_add_f32_e64 v67, v163, -v75
	v_cvt_pk_bf16_f32 v64, v72, v73
	v_cvt_pk_bf16_f32 v65, v66, v67
	v_cvt_pk_bf16_f32 v66, v68, v69
	v_cvt_pk_bf16_f32 v67, v70, v71
	v_pk_mul_f32 v[12:13], v[12:13], v[160:161] op_sel_hi:[1,0]
	v_pk_mul_f32 v[10:11], v[10:11], v[160:161] op_sel_hi:[1,0]
	v_mfma_f32_32x32x16_bf16 v[96:111], v[136:139], v[64:67], v[96:111]
	v_mul_f32_e64 v8, v8, v160
	v_mul_f32_e64 v9, v9, v160
	v_mul_f32_e64 v6, v6, v160
	v_mul_f32_e64 v7, v7, v160
	v_mul_f32_e64 v4, v4, v160
	v_mul_f32_e64 v5, v5, v160
	v_pk_mul_f32 v[2:3], v[2:3], v[160:161] op_sel_hi:[1,0]
	v_pk_mul_f32 v[0:1], v[0:1], v[160:161] op_sel_hi:[1,0]
	v_add_u32_e32 v72, s4, v116
	v_add_u32_e32 v73, 0x400, v72
	s_nop 1
	v_cvt_pk_bf16_f32 v64, v96, v97
	v_cvt_pk_bf16_f32 v65, v98, v99
	v_cvt_pk_bf16_f32 v66, v100, v101
	v_cvt_pk_bf16_f32 v67, v102, v103
	v_cvt_pk_bf16_f32 v68, v104, v105
	v_cvt_pk_bf16_f32 v69, v106, v107
	v_mfma_f32_32x32x16_bf16 v[48:63], v[144:147], v[64:67], v[48:63]
	v_cvt_pk_bf16_f32 v70, v108, v109
	v_cvt_pk_bf16_f32 v71, v110, v111
	v_add_u32_e32 v74, 0x1000, v72
	v_add_u32_e32 v75, 0x1400, v72
	v_add_u32_e32 v76, 0x2000, v72
	v_add_u32_e32 v77, 0x2400, v72
	v_add_u32_e32 v78, 0x3000, v72
	v_mfma_f32_32x32x16_bf16 v[32:47], v[148:151], v[64:67], v[32:47]
	v_add_u32_e32 v79, 0x3400, v72
	v_mfma_f32_32x32x16_bf16 v[16:31], v[128:131], v[64:67], v[16:31]
	v_mfma_f32_32x32x16_bf16 v[0:15], v[152:155], v[64:67], v[0:15]
	v_mfma_f32_32x32x16_bf16 v[80:95], v[140:143], v[64:67], v[80:95]
	s_waitcnt lgkmcnt(0)
	v_mfma_f32_32x32x16_bf16 v[48:63], v[176:179], v[68:71], v[48:63]
	v_mfma_f32_32x32x16_bf16 v[32:47], v[180:183], v[68:71], v[32:47]
	v_mfma_f32_32x32x16_bf16 v[16:31], v[184:187], v[68:71], v[16:31]
	v_mfma_f32_32x32x16_bf16 v[80:95], v[188:191], v[68:71], v[80:95]
	s_nop 11
	ds_write2_b32 v72, v80, v81 offset1:132
	ds_write2_b32 v73, v82, v83 offset0:8 offset1:140
	ds_write2_b32 v74, v84, v85 offset0:32 offset1:164
	ds_write2_b32 v75, v86, v87 offset0:40 offset1:172
	ds_write2_b32 v76, v88, v89 offset0:64 offset1:196
	ds_write2_b32 v77, v90, v91 offset0:72 offset1:204
	ds_write2_b32 v78, v92, v93 offset0:96 offset1:228
	ds_write2_b32 v79, v94, v95 offset0:104 offset1:236
	v_mfma_f32_32x32x16_bf16 v[0:15], v[156:159], v[68:71], v[0:15]
	s_waitcnt lgkmcnt(0)
	s_barrier
	s_cbranch_scc1 .LBB0_1833
	s_andn2_saveexec_b64 s[6:7], s[6:7]
	s_cbranch_execz .LBB0_1818
